# as v22 but no s_setprio raise in GQA attention phase (kept in diff-attn phase where it pairs with the wave-half DMA stagger)
# speedup vs baseline: 1.0110x; 1.0009x over previous
; __device__ __forceinline__ int fresh_lane() { int l; asm volatile("v_mbcnt_lo_u32_b32 %0, -1, 0\n\tv_mbcnt_hi_u32_b32 %0, -1, %0" : "=v"(l)); return l; }
; __device__ __forceinline__ void phase_attn_a(const Args& a, int L, char* lds, int wv, int bid) {
;   const bf16_t* proj = (const bf16_t*)(a.ws + WS_PROJ); unsigned char* ao = (unsigned char*)(a.ws + WS_XN);
;   float nbC;
;   { const int lane = fresh_lane(); const float* qg = a.in[4] + (L >> 1) * 128; const float* kg = a.in[5] + (L >> 1) * 128;
;     const float gq = wave_max(fmaxf(fabsf(qg[lane]), fabsf(qg[lane + 64]))), gk = wave_max(fmaxf(fabsf(kg[lane]), fabsf(kg[lane + 64])));
;     nbC = -(128.f * gq * gk * 1.02f) * (att::SCALE * 1.4426950408889634f); }
;   for (int vw = bid; vw < 256; vw += gridDim.x) {
;     const int xcd = vw & 7, w = vw >> 3;
;     for (int i = 0; i < 12; ++i) {
;       int b, kvh, hl, qb, seq; long seq0;
;       if (i < 4) { const int idx = i * 32 + w; b = xcd >> 2; kvh = xcd & 3; hl = idx >> 5; qb = idx & 31; seq = SEQ_S; seq0 = MP + (long)b * SEQ_S; }
;       else { const int i2 = i - 4, pair = xcd * 4 + (i2 >> 1), idx = (i2 & 1) * 32 + w; b = pair >> 2; kvh = pair & 3; hl = idx >> 4; qb = idx & 15; seq = SEQ_P; seq0 = (long)b * SEQ_P; }
;       const int h = kvh * 4 + hl; const long row0 = seq0 + qb * 256;
;       att::EpiA E{proj + row0 * A_IN + 3072 + h * 128, ao + row0 * DM + h * 128};
;       att::attn_gqa_body<A_IN, att::EpiA>(proj + row0 * A_IN + h * 128, proj + seq0 * A_IN + 2048 + kvh * 128, proj + seq0 * A_IN + 2560 + kvh * 128, seq, lds, nbC, E, wv, a.in[4] + (L >> 1) * 128, qb * 256, inv64_tab);
;     }
;   }
.LBB0_32:
	s_andn2_b64 vcc, exec, s[0:1]
	s_cbranch_vccnz .LBB0_47
	v_readlane_b32 s0, v253, 3
	s_cmp_lt_u32 s0, 4
	s_branch .Lprio_a_skip
	s_setprio 1
